# adds: mlstm_scan gate loads software-pipelined one block ahead (scan workgroups were late into their in-projection tiles)
# baseline (speedup 1.0000x reference)
; #define LAS __attribute__((address_space(3)))
; __device__ __forceinline__ float logsigmoid_(float x) { return fminf(x, 0.f) - log1pf(expf(-fabsf(x))); }
; __device__ __forceinline__ void mlstm_scan(const Frame& F, int hh) {
;     LAS float* sB = (LAS float*)F.lds;
;     LAS float* sW = sB + SP;
;     LAS float* sM = sW + SP;
;     LAS float* tot = sM + SP;
;     const float* gates = (const float*)(F.ws + WS_GATES);
;     const float big = F.in[15][hh], bfg = F.in[16][hh];
;     float cB = 0.f, cM = -INFINITY;
;     for (int it = 0; it < 16; ++it) { const int t = F.wave * 1024 + it * 64 + F.lane;
;         const float li = gates[(size_t)t * 8 + hh] + big; float v = logsigmoid_(gates[(size_t)t * 8 + 4 + hh] + bfg);
.LBB0_254:
	s_cmp_lt_i32 s86, 4
	s_cselect_b64 s[4:5], -1, 0
	s_and_b64 s[14:15], s[4:5], s[2:3]
	s_andn2_b64 vcc, exec, s[14:15]
	s_cbranch_vccnz .LBB0_296
	s_add_i32 s2, s88, -4
	s_cmp_lt_i32 s33, s2
	s_cbranch_scc1 .LBB0_272
	s_load_dwordx16 s[36:51], s[0:1], 0x40
	s_waitcnt lgkmcnt(0)
	s_sub_i32 s18, s33, s2
	s_mov_b32 s19, 0
	s_lshl_b64 s[16:17], s[18:19], 2
	s_waitcnt vmcnt(0)
	v_mov_b32_e32 v1, 0
	s_mov_b64 s[30:31], s[50:51]
	s_load_dwordx16 s[36:51], s[0:1], 0x80
	s_add_u32 s2, s30, s16
	s_addc_u32 s3, s31, s17
	v_mbcnt_lo_u32_b32 v2, -1, 0
	v_mbcnt_hi_u32_b32 v2, -1, v2
	s_waitcnt lgkmcnt(0)
	s_mov_b64 s[8:9], s[36:37]
	s_add_u32 s4, s8, s16
	s_addc_u32 s5, s9, s17
	global_load_dword v0, v1, s[2:3]
	global_load_dword v8, v1, s[4:5]
	v_bfrev_b32_e32 v4, 0.5
	v_and_b32_e32 v3, 64, v2
	v_lshl_or_b32 v9, v2, 2, v4
	v_add_u32_e32 v4, -1, v2
	v_cmp_lt_i32_e32 vcc, v4, v3
	s_mov_b64 s[12:13], s[40:41]
	s_lshl_b32 s22, s80, 10
	v_cndmask_b32_e32 v4, v4, v2, vcc
	v_lshlrev_b32_e32 v10, 2, v4
	v_add_u32_e32 v4, -2, v2
	v_cmp_lt_i32_e64 s[2:3], v4, v3
	s_add_u32 s12, s84, s16
	s_addc_u32 s13, s85, s17
	v_cndmask_b32_e64 v4, v4, v2, s[2:3]
	v_lshlrev_b32_e32 v11, 2, v4
	v_add_u32_e32 v4, -4, v2
	v_cmp_lt_i32_e64 s[4:5], v4, v3
	s_mov_b64 s[10:11], s[38:39]
	s_add_u32 s20, s12, 0xb90c000
	v_cndmask_b32_e64 v4, v4, v2, s[4:5]
	v_lshlrev_b32_e32 v12, 2, v4
	v_add_u32_e32 v4, -8, v2
	v_cmp_lt_i32_e64 s[6:7], v4, v3
	s_addc_u32 s21, s13, 0
	s_lshl_b32 s12, s80, 12
	v_cndmask_b32_e64 v4, v4, v2, s[6:7]
	v_lshlrev_b32_e32 v13, 2, v4
	v_add_u32_e32 v4, -16, v2
	v_cmp_lt_i32_e64 s[8:9], v4, v3
	s_add_i32 s12, s12, 0
	v_cmp_eq_u32_e32 vcc, 0, v160
	v_cndmask_b32_e64 v4, v4, v2, s[8:9]
	v_lshlrev_b32_e32 v14, 2, v4
	v_subrev_u32_e32 v4, 32, v2
	v_cmp_lt_i32_e64 s[10:11], v4, v3
	v_cmp_gt_u32_e64 s[2:3], 2, v160
	v_cmp_gt_u32_e64 s[4:5], 4, v160
	v_cndmask_b32_e64 v2, v4, v2, s[10:11]
	v_cmp_gt_u32_e64 s[6:7], 8, v160
	v_cmp_gt_u32_e64 s[8:9], 16, v160
	v_lshlrev_b32_e32 v15, 2, v2
	v_cmp_gt_u32_e64 s[10:11], 32, v160
	v_lshl_add_u32 v16, v160, 2, s12
	v_or_b32_e32 v2, s22, v160
	v_mov_b32_e32 v19, 0xff800000
	s_mov_b32 s23, 0xbfb8aa3b
	s_mov_b32 s24, 0xb2a5705f
	s_mov_b32 s25, 0x42ce8ed0
	s_mov_b32 s26, 0xc2b17218
	s_mov_b32 s27, 0x7f800000
	v_mov_b32_e32 v17, 0x7f800000
	s_mov_b32 s28, 0x3f2aaaab
	v_mov_b32_e32 v18, 0x3ecc95a3
	s_mov_b32 s29, 0x3f317218
	s_mov_b32 s30, 0x33800000
	v_mov_b32_e32 v4, 0x3f317218
	v_ashrrev_i32_e32 v41, 31, v2
	v_mov_b32_e32 v40, v2
	v_lshlrev_b64 v[40:41], 5, v[40:41]
	v_lshl_add_u64 v[40:41], s[20:21], 0, v[40:41]
	global_load_dword v38, v[40:41], off offset:16
	global_load_dword v39, v[40:41], off
; __device__ __forceinline__ float logsigmoid_(float x) { return fminf(x, 0.f) - log1pf(expf(-fabsf(x))); }
; __device__ __forceinline__ void mlstm_scan(const Frame& F, int hh) {
;     ...
;     for (int it = 0; it < 16; ++it) { const int t = F.wave * 1024 + it * 64 + F.lane;
;         const float li = gates[(size_t)t * 8 + hh] + big; float v = logsigmoid_(gates[(size_t)t * 8 + 4 + hh] + bfg);
; #pragma unroll
;         for (int d = 1; d < 64; d <<= 1) { const float o = __shfl_up(v, d); if (F.lane >= d) v += o; }
;         const float Bl = cB + v; const float wl = li - Bl; float mx = wl;
; #pragma unroll
;         for (int d = 1; d < 64; d <<= 1) { const float o = __shfl_up(mx, d); if (F.lane >= d) mx = fmaxf(mx, o); }
;         mx = fmaxf(mx, cM);
;         sB[t] = Bl; sW[t] = wl; sM[t] = mx;
;         cB = __shfl(Bl, 63); cM = __shfl(mx, 63); }
.LBB0_257:
	s_waitcnt vmcnt(0)
	v_mov_b32_e32 v3, v38
	v_mov_b32_e32 v6, v39
	v_add_u32_e32 v2, 64, v2
	v_ashrrev_i32_e32 v41, 31, v2
	v_mov_b32_e32 v40, v2
	v_lshlrev_b64 v[40:41], 5, v[40:41]
	v_lshl_add_u64 v[40:41], s[20:21], 0, v[40:41]
	global_load_dword v38, v[40:41], off offset:16
	global_load_dword v39, v[40:41], off
	v_add_f32_e32 v3, v8, v3
	v_mul_f32_e64 v5, |v3|, s23
	v_fma_f32 v20, |v3|, s23, -v5
	v_rndne_f32_e32 v21, v5
	v_fma_f32 v20, |v3|, s24, v20
	v_sub_f32_e32 v5, v5, v21
	v_add_f32_e32 v5, v5, v20
	v_cvt_i32_f32_e32 v21, v21
	v_exp_f32_e32 v5, v5
	v_cmp_ngt_f32_e64 s[12:13], |v3|, s25
	v_min_f32_e32 v7, 0, v3
	v_ldexp_f32 v5, v5, v21
	v_cndmask_b32_e64 v5, 0, v5, s[12:13]
	v_cmp_nlt_f32_e64 s[12:13], |v3|, s26
	s_nop 1
	v_cndmask_b32_e64 v3, v17, v5, s[12:13]
	v_add_f32_e32 v5, 1.0, v3
	v_add_f32_e32 v22, -1.0, v5
	v_frexp_mant_f32_e32 v23, v5
	v_cvt_f64_f32_e32 v[20:21], v5
	v_sub_f32_e32 v24, v22, v5
	v_frexp_exp_i32_f64_e32 v20, v[20:21]
	v_cmp_gt_f32_e64 s[12:13], s28, v23
	v_sub_f32_e32 v22, v3, v22
	v_add_f32_e32 v21, 1.0, v24
	v_subbrev_co_u32_e64 v20, s[12:13], 0, v20, s[12:13]
	v_add_f32_e32 v21, v22, v21
	v_sub_u32_e32 v22, 0, v20
	v_ldexp_f32 v5, v5, v22
	v_ldexp_f32 v21, v21, v22
	v_add_f32_e32 v22, -1.0, v5
	v_add_f32_e32 v24, 1.0, v5
	v_add_f32_e32 v23, 1.0, v22
	v_add_f32_e32 v25, -1.0, v24
	v_sub_f32_e32 v23, v5, v23
	v_sub_f32_e32 v5, v5, v25
	v_add_f32_e32 v5, v21, v5
	v_add_f32_e32 v25, v21, v23
	v_add_f32_e32 v21, v24, v5
	v_rcp_f32_e32 v28, v21
	v_add_f32_e32 v23, v22, v25
	v_sub_f32_e32 v24, v24, v21
	v_add_f32_e32 v5, v5, v24
	v_mul_f32_e32 v30, v23, v28
	v_mul_f32_e32 v24, v21, v30
	v_fma_f32 v26, v30, v21, -v24
	v_sub_f32_e32 v22, v22, v23
	v_fmac_f32_e32 v26, v30, v5
	v_add_f32_e32 v29, v25, v22
	v_add_f32_e32 v22, v24, v26
	v_sub_f32_e32 v25, v23, v22
	v_mov_b32_e32 v27, v22
	v_pk_add_f32 v[22:23], v[22:23], v[24:25] neg_lo:[0,1] neg_hi:[0,1]
	v_cvt_f32_i32_e32 v20, v20
	v_pk_add_f32 v[22:23], v[22:23], v[26:27] neg_lo:[0,1] neg_hi:[0,1]
	v_cmp_neq_f32_e64 s[12:13], s27, v3
	v_add_f32_e32 v23, v29, v23
	v_add_f32_e32 v22, v22, v23
	v_add_f32_e32 v23, v25, v22
	v_mul_f32_e32 v27, v28, v23
	v_mul_f32_e32 v24, v21, v27
	v_fma_f32 v26, v27, v21, -v24
	v_sub_f32_e32 v25, v25, v23
	v_fmac_f32_e32 v26, v27, v5
	v_add_f32_e32 v29, v22, v25
	v_add_f32_e32 v31, v30, v27
	v_add_f32_e32 v22, v24, v26
	v_sub_f32_e32 v21, v31, v30
	v_sub_f32_e32 v25, v23, v22
	v_sub_f32_e32 v5, v27, v21
	v_mov_b32_e32 v27, v22
	v_pk_add_f32 v[22:23], v[22:23], v[24:25] neg_lo:[0,1] neg_hi:[0,1]
	s_nop 0
	v_pk_add_f32 v[22:23], v[22:23], v[26:27] neg_lo:[0,1] neg_hi:[0,1]
	s_nop 0
	v_add_f32_e32 v21, v29, v23
	v_add_f32_e32 v21, v22, v21
	v_add_f32_e32 v21, v25, v21
	v_mul_f32_e32 v21, v28, v21
	v_add_f32_e32 v5, v5, v21
	v_add_f32_e32 v21, v31, v5
	v_mul_f32_e32 v22, v21, v21
	v_sub_f32_e32 v24, v21, v31
	v_fmamk_f32 v25, v22, 0x3e9b6dac, v18
	v_ldexp_f32 v23, v21, 1
	v_sub_f32_e32 v24, v5, v24
	v_mul_f32_e32 v21, v21, v22
	v_fmaak_f32 v5, v22, v25, 0x3f2aaada
	v_ldexp_f32 v27, v24, 1
	v_pk_mul_f32 v[24:25], v[20:21], v[4:5]
	s_nop 0
	v_fma_f32 v22, v20, s29, -v24
	v_fmac_f32_e32 v22, 0xb102e308, v20
	v_pk_add_f32 v[20:21], v[24:25], v[22:23]
	v_mov_b32_e32 v26, v24
	v_sub_f32_e32 v5, v21, v23
	v_sub_f32_e32 v5, v25, v5
	v_add_f32_e32 v27, v27, v5
	v_pk_add_f32 v[28:29], v[20:21], v[24:25] neg_lo:[0,1] neg_hi:[0,1]
	v_pk_add_f32 v[24:25], v[20:21], v[26:27]
	v_mov_b32_e32 v23, v20
	v_mov_b32_e32 v29, v25
	v_pk_add_f32 v[32:33], v[22:23], v[28:29] neg_lo:[0,1] neg_hi:[0,1]
	v_pk_add_f32 v[22:23], v[22:23], v[28:29]
	v_mov_b32_e32 v31, v20
	v_pk_add_f32 v[28:29], v[22:23], v[20:21] op_sel:[1,0] op_sel_hi:[0,1] neg_lo:[0,1] neg_hi:[0,1]
	v_mov_b32_e32 v30, v27
	v_mov_b32_e32 v26, v25
	v_mov_b32_e32 v27, v23
	v_pk_mov_b32 v[20:21], v[20:21], v[28:29] op_sel:[1,0]
	v_pk_add_f32 v[24:25], v[24:25], v[28:29] op_sel_hi:[1,0] neg_lo:[0,1] neg_hi:[0,1]
	v_pk_add_f32 v[20:21], v[26:27], v[20:21] neg_lo:[0,1] neg_hi:[0,1]
	v_mov_b32_e32 v24, v32
	v_pk_add_f32 v[20:21], v[30:31], v[20:21] neg_lo:[0,1] neg_hi:[0,1]
	v_mov_b32_e32 v33, v23
	v_pk_add_f32 v[24:25], v[24:25], v[20:21]
	s_nop 0
	v_pk_add_f32 v[26:27], v[24:25], v[24:25] op_sel:[0,1] op_sel_hi:[1,0]
	s_nop 0
	v_pk_add_f32 v[22:23], v[22:23], v[26:27] op_sel:[1,0] op_sel_hi:[0,1]
	v_mov_b32_e32 v25, v22
	v_mov_b32_e32 v21, v26
	v_pk_add_f32 v[26:27], v[24:25], v[32:33] neg_lo:[0,1] neg_hi:[0,1]
	s_nop 0
	v_sub_f32_e32 v5, v24, v26
	v_pk_add_f32 v[20:21], v[20:21], v[26:27] neg_lo:[0,1] neg_hi:[0,1]
	v_sub_f32_e32 v5, v32, v5
	v_add_f32_e32 v5, v20, v5
	v_add_f32_e32 v5, v5, v21
	v_add_f32_e32 v5, v22, v5
	v_cndmask_b32_e64 v5, v17, v5, s[12:13]
	v_cmp_lt_f32_e64 s[12:13], |v3|, s30
	v_add_u32_e32 v20, s19, v16
	s_addk_i32 s19, 0x100
	v_cndmask_b32_e64 v3, v5, v3, s[12:13]
	v_sub_f32_e32 v3, v7, v3
	ds_bpermute_b32 v5, v10, v3
	s_cmpk_eq_i32 s19, 0x1000
	v_add_u32_e32 v21, 0x10000, v20
	s_waitcnt lgkmcnt(0)
	v_add_f32_e32 v5, v3, v5
	v_cndmask_b32_e32 v3, v5, v3, vcc
	ds_bpermute_b32 v5, v11, v3
	s_waitcnt lgkmcnt(0)
	v_add_f32_e32 v5, v3, v5
	v_cndmask_b32_e64 v3, v5, v3, s[2:3]
	ds_bpermute_b32 v5, v12, v3
	s_waitcnt lgkmcnt(0)
	v_add_f32_e32 v5, v3, v5
	v_cndmask_b32_e64 v3, v5, v3, s[4:5]
	ds_bpermute_b32 v5, v13, v3
	s_waitcnt lgkmcnt(0)
	v_add_f32_e32 v5, v3, v5
	v_cndmask_b32_e64 v3, v5, v3, s[6:7]
	ds_bpermute_b32 v5, v14, v3
	s_waitcnt lgkmcnt(0)
	v_add_f32_e32 v5, v3, v5
	v_cndmask_b32_e64 v3, v5, v3, s[8:9]
	ds_bpermute_b32 v5, v15, v3
	s_waitcnt lgkmcnt(0)
	v_add_f32_e32 v5, v3, v5
	v_cndmask_b32_e64 v7, v5, v3, s[10:11]
	s_nop 0
	v_pk_add_f32 v[6:7], v[0:1], v[6:7]
	s_nop 0
	v_sub_f32_e32 v3, v6, v7
	ds_bpermute_b32 v1, v10, v3
	v_max_f32_e32 v6, v19, v19
	s_waitcnt lgkmcnt(0)
	v_max_f32_e32 v1, v1, v1
	v_max_f32_e32 v1, v3, v1
	v_cndmask_b32_e32 v1, v1, v3, vcc
	ds_bpermute_b32 v5, v11, v1
	s_waitcnt lgkmcnt(0)
	v_max_f32_e32 v5, v5, v5
	v_max_f32_e32 v5, v1, v5
	v_cndmask_b32_e64 v1, v5, v1, s[2:3]
	ds_bpermute_b32 v5, v12, v1
	s_waitcnt lgkmcnt(0)
	v_max_f32_e32 v5, v5, v5
	v_max_f32_e32 v5, v1, v5
	v_cndmask_b32_e64 v1, v5, v1, s[4:5]
	ds_bpermute_b32 v5, v13, v1
	s_waitcnt lgkmcnt(0)
	v_max_f32_e32 v5, v5, v5
	v_max_f32_e32 v5, v1, v5
	v_cndmask_b32_e64 v1, v5, v1, s[6:7]
	ds_bpermute_b32 v5, v14, v1
	s_waitcnt lgkmcnt(0)
	v_max_f32_e32 v5, v5, v5
	v_max_f32_e32 v5, v1, v5
	v_cndmask_b32_e64 v5, v5, v1, s[8:9]
	ds_bpermute_b32 v19, v15, v5
	v_max_f32_e32 v22, v5, v5
	ds_bpermute_b32 v1, v9, v7
	s_waitcnt lgkmcnt(1)
	v_max_f32_e32 v19, v19, v19
	v_max_f32_e32 v19, v22, v19
	v_cndmask_b32_e64 v5, v19, v5, s[10:11]
	v_max_f32_e32 v5, v5, v5
	v_max_f32_e32 v5, v5, v6
	ds_bpermute_b32 v19, v9, v5
	ds_write2st64_b32 v20, v7, v3 offset1:128
	ds_write_b32 v21, v5
	s_cbranch_scc0 .LBB0_257
	s_waitcnt vmcnt(0)
	s_and_saveexec_b64 s[2:3], vcc
	s_cbranch_execz .LBB0_260
	s_lshl_b32 s4, s80, 2
	s_add_i32 s4, s4, 0
	s_add_i32 s4, s4, 0x18000
	v_mov_b32_e32 v0, s4
	s_waitcnt lgkmcnt(2)
	ds_write2_b32 v0, v1, v19 offset1:8
